# plus non-temporal reads of YL in the RG-LRU carry pass (read once, then overwritten in place)
# baseline (speedup 1.0000x reference)
; __device__ __forceinline__ u32x4 pack8(f32x4 a, f32x4 b) { u32x4 w; w.x = cvt_pk(a[0], a[1]); w.y = cvt_pk(a[2], a[3]); w.z = cvt_pk(b[0], b[1]); w.w = cvt_pk(b[2], b[3]); return w; }
; __device__ __forceinline__ void lru_light(const Ptrs& P, int wu, int lane) {
;     ...
;     const size_t base = ((size_t)b * SEQ + chunk * 128 + (lane >> 3)) * DM + ch0;
; #pragma unroll 4
;     for (int i = 0; i < 16; ++i) { const size_t o = base + (size_t)(8 * i) * DM;
;         const u32x4 y = *(const u32x4*)(YL + o), p = *(const u32x4*)(PU + o);
;         f32x4 v0, v1;
;         v0[0] = bflo(y.x) + bflo(p.x) * s0[0]; v0[1] = bfhi(y.x) + bfhi(p.x) * s0[1]; v0[2] = bflo(y.y) + bflo(p.y) * s0[2]; v0[3] = bfhi(y.y) + bfhi(p.y) * s0[3];
;         v1[0] = bflo(y.z) + bflo(p.z) * s1[0]; v1[1] = bfhi(y.z) + bfhi(p.z) * s1[1]; v1[2] = bflo(y.w) + bflo(p.w) * s1[2]; v1[3] = bfhi(y.w) + bfhi(p.w) * s1[3];
;         *(u32x4*)(YL + o) = pack8(v0, v1); }
.LBB0_576:
	v_lshl_add_u64 v[2:3], v[0:1], 0, s[4:5]
	s_mov_b32 s6, 0x3804000
	v_add_co_u32_e64 v38, s[6:7], s6, v2
	s_mov_b32 s8, 0x7804000
	s_nop 0
	v_addc_co_u32_e64 v39, s[6:7], 0, v3, s[6:7]
	v_add_co_u32_e64 v8, s[6:7], s8, v2
	s_mov_b32 s9, 0x3808000
	s_nop 0
	v_addc_co_u32_e64 v9, s[6:7], 0, v3, s[6:7]
	v_add_co_u32_e64 v40, s[6:7], s9, v2
	s_mov_b32 s12, 0x7808000
	s_nop 0
	v_addc_co_u32_e64 v41, s[6:7], 0, v3, s[6:7]
	v_add_co_u32_e64 v16, s[6:7], s12, v2
	s_mov_b32 s13, 0x380c000
	s_nop 0
	v_addc_co_u32_e64 v17, s[6:7], 0, v3, s[6:7]
	v_add_co_u32_e64 v42, s[6:7], s13, v2
	s_mov_b32 s14, 0x780c000
	v_add_co_u32_e32 v36, vcc, 0x3800000, v2
	v_addc_co_u32_e64 v43, s[6:7], 0, v3, s[6:7]
	v_add_co_u32_e64 v24, s[6:7], s14, v2
	v_addc_co_u32_e32 v37, vcc, 0, v3, vcc
	s_nop 0
	v_addc_co_u32_e64 v25, s[6:7], 0, v3, s[6:7]
	v_add_co_u32_e32 v2, vcc, 0x7800000, v2
	global_load_dwordx4 v[4:7], v[38:39], off nt
	s_nop 0
	global_load_dwordx4 v[8:11], v[8:9], off nt
	s_nop 0
	global_load_dwordx4 v[12:15], v[40:41], off nt
	s_nop 0
	global_load_dwordx4 v[16:19], v[16:17], off nt
	s_nop 0
	global_load_dwordx4 v[20:23], v[42:43], off nt
	s_nop 0
	global_load_dwordx4 v[24:27], v[24:25], off nt
	v_addc_co_u32_e32 v3, vcc, 0, v3, vcc
	global_load_dwordx4 v[28:31], v[36:37], off nt
	global_load_dwordx4 v[32:35], v[2:3], off nt
	s_add_u32 s4, s4, 0x10000
	s_addc_u32 s5, s5, 0
	s_cmp_lg_u32 s4, 0x40000
	s_waitcnt vmcnt(7)
	v_lshlrev_b32_e32 v2, 16, v4
	v_and_b32_e32 v3, 0xffff0000, v4
	s_waitcnt vmcnt(6)
	v_lshlrev_b32_e32 v44, 16, v8
	v_and_b32_e32 v45, 0xffff0000, v8
	v_lshlrev_b32_e32 v4, 16, v5
	v_and_b32_e32 v5, 0xffff0000, v5
	v_lshlrev_b32_e32 v8, 16, v9
	v_and_b32_e32 v9, 0xffff0000, v9
	v_lshlrev_b32_e32 v46, 16, v6
	v_and_b32_e32 v47, 0xffff0000, v6
	v_lshlrev_b32_e32 v48, 16, v10
	v_and_b32_e32 v49, 0xffff0000, v10
	v_lshlrev_b32_e32 v6, 16, v7
	v_and_b32_e32 v7, 0xffff0000, v7
	v_lshlrev_b32_e32 v10, 16, v11
	v_and_b32_e32 v11, 0xffff0000, v11
	s_waitcnt vmcnt(5)
	v_lshlrev_b32_e32 v50, 16, v12
	v_and_b32_e32 v51, 0xffff0000, v12
	s_waitcnt vmcnt(4)
	v_lshlrev_b32_e32 v52, 16, v16
	v_and_b32_e32 v53, 0xffff0000, v16
	v_lshlrev_b32_e32 v12, 16, v13
	v_and_b32_e32 v13, 0xffff0000, v13
	v_lshlrev_b32_e32 v16, 16, v17
	v_and_b32_e32 v17, 0xffff0000, v17
	v_lshlrev_b32_e32 v54, 16, v14
	v_and_b32_e32 v55, 0xffff0000, v14
	v_lshlrev_b32_e32 v56, 16, v18
	v_and_b32_e32 v57, 0xffff0000, v18
	v_lshlrev_b32_e32 v14, 16, v15
	v_and_b32_e32 v15, 0xffff0000, v15
	v_lshlrev_b32_e32 v18, 16, v19
	v_and_b32_e32 v19, 0xffff0000, v19
	s_waitcnt vmcnt(3)
	v_lshlrev_b32_e32 v58, 16, v20
	v_and_b32_e32 v59, 0xffff0000, v20
	s_waitcnt vmcnt(2)
	v_lshlrev_b32_e32 v60, 16, v24
	v_and_b32_e32 v61, 0xffff0000, v24
	v_lshlrev_b32_e32 v20, 16, v21
	v_and_b32_e32 v21, 0xffff0000, v21
	v_lshlrev_b32_e32 v24, 16, v25
	v_and_b32_e32 v25, 0xffff0000, v25
	v_lshlrev_b32_e32 v62, 16, v22
	v_and_b32_e32 v63, 0xffff0000, v22
	v_lshlrev_b32_e32 v72, 16, v26
	v_and_b32_e32 v73, 0xffff0000, v26
	v_lshlrev_b32_e32 v22, 16, v23
	v_and_b32_e32 v23, 0xffff0000, v23
	v_lshlrev_b32_e32 v26, 16, v27
	v_and_b32_e32 v27, 0xffff0000, v27
	s_waitcnt vmcnt(1)
	v_lshlrev_b32_e32 v74, 16, v28
	v_and_b32_e32 v75, 0xffff0000, v28
	v_lshlrev_b32_e32 v28, 16, v29
	v_and_b32_e32 v29, 0xffff0000, v29
	v_lshlrev_b32_e32 v76, 16, v30
	v_and_b32_e32 v77, 0xffff0000, v30
	v_lshlrev_b32_e32 v30, 16, v31
	v_and_b32_e32 v31, 0xffff0000, v31
	v_pk_fma_f32 v[2:3], v[64:65], v[44:45], v[2:3]
	v_pk_fma_f32 v[4:5], v[66:67], v[8:9], v[4:5]
	v_pk_fma_f32 v[8:9], v[68:69], v[48:49], v[46:47]
	v_pk_fma_f32 v[6:7], v[70:71], v[10:11], v[6:7]
	v_pk_fma_f32 v[10:11], v[64:65], v[52:53], v[50:51]
	v_pk_fma_f32 v[12:13], v[66:67], v[16:17], v[12:13]
	v_pk_fma_f32 v[16:17], v[68:69], v[56:57], v[54:55]
	v_pk_fma_f32 v[14:15], v[70:71], v[18:19], v[14:15]
	v_pk_fma_f32 v[18:19], v[64:65], v[60:61], v[58:59]
	v_pk_fma_f32 v[20:21], v[66:67], v[24:25], v[20:21]
	v_pk_fma_f32 v[22:23], v[70:71], v[26:27], v[22:23]
	s_waitcnt vmcnt(0)
	v_lshlrev_b32_e32 v26, 16, v32
	v_and_b32_e32 v27, 0xffff0000, v32
	v_lshlrev_b32_e32 v32, 16, v33
	v_and_b32_e32 v33, 0xffff0000, v33
	v_lshlrev_b32_e32 v44, 16, v34
	v_and_b32_e32 v45, 0xffff0000, v34
	v_lshlrev_b32_e32 v34, 16, v35
	v_and_b32_e32 v35, 0xffff0000, v35
	v_pk_fma_f32 v[24:25], v[68:69], v[72:73], v[62:63]
	v_cvt_pk_bf16_f32 v2, v2, v3
	v_cvt_pk_bf16_f32 v3, v4, v5
	v_cvt_pk_bf16_f32 v4, v8, v9
	v_cvt_pk_bf16_f32 v5, v6, v7
	v_cvt_pk_bf16_f32 v6, v10, v11
	v_cvt_pk_bf16_f32 v8, v16, v17
	v_cvt_pk_bf16_f32 v9, v14, v15
	v_cvt_pk_bf16_f32 v10, v18, v19
	v_cvt_pk_bf16_f32 v11, v20, v21
	v_pk_fma_f32 v[14:15], v[64:65], v[26:27], v[74:75]
	v_pk_fma_f32 v[16:17], v[66:67], v[32:33], v[28:29]
	v_pk_fma_f32 v[18:19], v[68:69], v[44:45], v[76:77]
	v_pk_fma_f32 v[20:21], v[70:71], v[34:35], v[30:31]
	v_cvt_pk_bf16_f32 v7, v12, v13
	v_cvt_pk_bf16_f32 v12, v24, v25
	v_cvt_pk_bf16_f32 v13, v22, v23
	global_store_dwordx4 v[38:39], v[2:5], off
	global_store_dwordx4 v[40:41], v[6:9], off
	global_store_dwordx4 v[42:43], v[10:13], off
	v_cvt_pk_bf16_f32 v2, v14, v15
	v_cvt_pk_bf16_f32 v3, v16, v17
	v_cvt_pk_bf16_f32 v4, v18, v19
	v_cvt_pk_bf16_f32 v5, v20, v21
	global_store_dwordx4 v[36:37], v[2:5], off
	s_cbranch_scc1 .LBB0_576
	s_branch .LBB0_565
